# prompt attention: the output-accumulator rescale uses scalar f32 multiplies instead of packed ones (same arithmetic)
# speedup vs baseline: 1.0024x; 1.0024x over previous
.LBB0_1070:
	s_cmp_gt_u32 s52, s24
	s_cbranch_scc1 .LBB0_1080
	s_bitcmp1_b32 s52, 0
	s_cselect_b32 s4, 0x9400, 0
	s_add_i32 s6, s4, 0
	s_add_i32 s4, s6, s37
	v_add3_u32 v190, s4, v180, v233
	ds_read_b128 v[144:147], v195
	ds_read_b128 v[148:151], v190
	ds_read_b128 v[196:199], v195 offset:32
	ds_read_b128 v[152:155], v190 offset:32
	ds_read_b128 v[200:203], v195 offset:64
	ds_read_b128 v[156:159], v190 offset:64
	ds_read_b128 v[204:207], v195 offset:96
	ds_read_b128 v[208:211], v190 offset:96
	ds_read_b128 v[212:215], v190 offset:8704
	ds_read_b128 v[216:219], v190 offset:8736
	ds_read_b128 v[220:223], v190 offset:8768
	ds_read_b128 v[224:227], v190 offset:8800
	s_add_i32 s7, s53, 0xffffffbf
	s_mov_b64 s[4:5], -1
	s_cmp_le_i32 s7, s40
	s_waitcnt lgkmcnt(10)
	v_mfma_f32_32x32x16_bf16 v[128:143], v[148:151], v[144:147], 0
	s_waitcnt lgkmcnt(8)
	v_mfma_f32_32x32x16_bf16 v[128:143], v[152:155], v[196:199], v[128:143]
	s_waitcnt lgkmcnt(6)
	v_mfma_f32_32x32x16_bf16 v[128:143], v[156:159], v[200:203], v[128:143]
	s_waitcnt lgkmcnt(4)
	v_mfma_f32_32x32x16_bf16 v[128:143], v[208:211], v[204:207], v[128:143]
	s_waitcnt lgkmcnt(3)
	v_mfma_f32_32x32x16_bf16 v[144:159], v[212:215], v[144:147], 0
	s_waitcnt lgkmcnt(2)
	v_mfma_f32_32x32x16_bf16 v[144:159], v[216:219], v[196:199], v[144:159]
	s_waitcnt lgkmcnt(1)
	v_mfma_f32_32x32x16_bf16 v[144:159], v[220:223], v[200:203], v[144:159]
	s_waitcnt lgkmcnt(0)
	v_mfma_f32_32x32x16_bf16 v[144:159], v[224:227], v[204:207], v[144:159]
	s_cbranch_scc0 .LBB0_1073
	s_add_i32 s4, 0, 0x27a00
	v_mov_b32_e32 v190, s4
	ds_read_b32 v190, v190
	s_mov_b64 s[4:5], 0
	v_mbcnt_lo_u32_b32 v191, -1, 0
	v_mbcnt_hi_u32_b32 v191, -1, v191
	v_lshlrev_b32_e32 v191, 2, v191
	v_xor_b32_e32 v191, 0x80, v191
	v_max3_f32 v196, v128, v129, v130
	v_max3_f32 v196, v196, v131, v132
	v_max3_f32 v196, v196, v133, v134
	v_max3_f32 v196, v196, v135, v136
	v_max3_f32 v196, v196, v137, v138
	v_max3_f32 v196, v196, v139, v140
	v_max3_f32 v196, v196, v141, v142
	v_max3_f32 v196, v196, v143, v144
	v_max3_f32 v196, v196, v145, v146
	v_max3_f32 v196, v196, v147, v148
	v_max3_f32 v196, v196, v149, v150
	v_max3_f32 v196, v196, v151, v152
	v_max3_f32 v196, v196, v153, v154
	v_max3_f32 v196, v196, v155, v156
	v_max3_f32 v196, v196, v157, v158
	v_max_f32_e32 v196, v196, v159
	ds_bpermute_b32 v191, v191, v196
	s_waitcnt lgkmcnt(0)
	v_max_f32_e32 v196, v196, v191
	v_fma_f32 v196, v196, s28, v190
	v_add_f32_e32 v197, 0x41000000, v194
	v_cmp_gt_f32_e32 vcc, v196, v197
	s_cbranch_vccz .Lat_far_nors_1
	v_max_f32_e32 v197, v194, v196
	v_sub_f32_e32 v198, v194, v197
	v_exp_f32_e32 v198, v198
	v_mov_b32_e32 v194, v197
	v_mul_f32_e32 v238, v238, v198
	v_mul_f32_e32 v126, v198, v126
	v_mul_f32_e32 v127, v198, v127
	v_mul_f32_e32 v124, v198, v124
	v_mul_f32_e32 v125, v198, v125
	v_mul_f32_e32 v122, v198, v122
	v_mul_f32_e32 v123, v198, v123
	v_mul_f32_e32 v120, v198, v120
	v_mul_f32_e32 v121, v198, v121
	v_mul_f32_e32 v118, v198, v118
	v_mul_f32_e32 v119, v198, v119
	v_mul_f32_e32 v116, v198, v116
	v_mul_f32_e32 v117, v198, v117
	v_mul_f32_e32 v114, v198, v114
	v_mul_f32_e32 v115, v198, v115
	v_mul_f32_e32 v112, v198, v112
	v_mul_f32_e32 v113, v198, v113
	v_mul_f32_e32 v94, v198, v94
	v_mul_f32_e32 v95, v198, v95
	v_mul_f32_e32 v92, v198, v92
	v_mul_f32_e32 v93, v198, v93
	v_mul_f32_e32 v90, v198, v90
	v_mul_f32_e32 v91, v198, v91
	v_mul_f32_e32 v88, v198, v88
	v_mul_f32_e32 v89, v198, v89
	v_mul_f32_e32 v86, v198, v86
	v_mul_f32_e32 v87, v198, v87
	v_mul_f32_e32 v84, v198, v84
	v_mul_f32_e32 v85, v198, v85
	v_mul_f32_e32 v82, v198, v82
	v_mul_f32_e32 v83, v198, v83
	v_mul_f32_e32 v80, v198, v80
	v_mul_f32_e32 v81, v198, v81
	v_mul_f32_e32 v62, v198, v62
	v_mul_f32_e32 v63, v198, v63
	v_mul_f32_e32 v60, v198, v60
	v_mul_f32_e32 v61, v198, v61
	v_mul_f32_e32 v58, v198, v58
	v_mul_f32_e32 v59, v198, v59
	v_mul_f32_e32 v56, v198, v56
	v_mul_f32_e32 v57, v198, v57
	v_mul_f32_e32 v54, v198, v54
	v_mul_f32_e32 v55, v198, v55
	v_mul_f32_e32 v52, v198, v52
	v_mul_f32_e32 v53, v198, v53
	v_mul_f32_e32 v50, v198, v50
	v_mul_f32_e32 v51, v198, v51
	v_mul_f32_e32 v48, v198, v48
	v_mul_f32_e32 v49, v198, v49
	v_mul_f32_e32 v30, v198, v30
	v_mul_f32_e32 v31, v198, v31
	v_mul_f32_e32 v28, v198, v28
	v_mul_f32_e32 v29, v198, v29
	v_mul_f32_e32 v26, v198, v26
	v_mul_f32_e32 v27, v198, v27
	v_mul_f32_e32 v24, v198, v24
	v_mul_f32_e32 v25, v198, v25
	v_mul_f32_e32 v22, v198, v22
	v_mul_f32_e32 v23, v198, v23
	v_mul_f32_e32 v20, v198, v20
	v_mul_f32_e32 v21, v198, v21
	v_mul_f32_e32 v18, v198, v18
	v_mul_f32_e32 v19, v198, v19
	v_mul_f32_e32 v16, v198, v16
	v_mul_f32_e32 v17, v198, v17

.LBB0_1075:
	s_nop 0
	v_max_f32_e32 v128, v227, v227
	v_max_f32_e32 v129, v226, v226
	v_max_f32_e32 v128, v129, v128
	v_max3_f32 v128, v128, v224, v225
	v_max3_f32 v128, v128, v222, v223
	v_max3_f32 v128, v128, v220, v221
	v_max3_f32 v128, v128, v218, v219
	v_max3_f32 v128, v128, v216, v217
	v_max3_f32 v128, v128, v214, v215
	v_max3_f32 v128, v128, v212, v213
	v_max3_f32 v128, v128, v210, v211
	v_max3_f32 v128, v128, v208, v209
	v_max3_f32 v128, v128, v206, v207
	v_max3_f32 v128, v128, v204, v205
	v_max3_f32 v128, v128, v202, v203
	v_max3_f32 v128, v128, v200, v201
	v_mbcnt_lo_u32_b32 v129, -1, 0
	v_mbcnt_hi_u32_b32 v129, -1, v129
	v_max3_f32 v128, v128, v198, v199
	v_lshlrev_b32_e32 v129, 2, v129
	v_max3_f32 v128, v128, v196, v197
	v_xor_b32_e32 v129, 0x80, v129
	ds_bpermute_b32 v129, v129, v128
	s_waitcnt lgkmcnt(0)
	v_max_f32_e32 v129, v129, v129
	v_max_f32_e32 v128, v128, v129
	v_add_f32_e32 v129, 0x41000000, v194
	v_cmp_gt_f32_e32 vcc, v128, v129
	s_cbranch_vccz .LBB0_1077
	v_max_f32_e32 v128, v128, v128
	v_max_f32_e32 v129, v194, v194
	v_max_f32_e32 v129, v129, v128
	v_sub_f32_e32 v128, v194, v129
	v_exp_f32_e32 v128, v128
	v_mov_b32_e32 v194, v129
	v_mul_f32_e32 v238, v238, v128
	v_mul_f32_e32 v126, v128, v126
	v_mul_f32_e32 v127, v128, v127
	v_mul_f32_e32 v124, v128, v124
	v_mul_f32_e32 v125, v128, v125
	v_mul_f32_e32 v122, v128, v122
	v_mul_f32_e32 v123, v128, v123
	v_mul_f32_e32 v120, v128, v120
	v_mul_f32_e32 v121, v128, v121
	v_mul_f32_e32 v118, v128, v118
	v_mul_f32_e32 v119, v128, v119
	v_mul_f32_e32 v116, v128, v116
	v_mul_f32_e32 v117, v128, v117
	v_mul_f32_e32 v114, v128, v114
	v_mul_f32_e32 v115, v128, v115
	v_mul_f32_e32 v112, v128, v112
	v_mul_f32_e32 v113, v128, v113
	v_mul_f32_e32 v94, v128, v94
	v_mul_f32_e32 v95, v128, v95
	v_mul_f32_e32 v92, v128, v92
	v_mul_f32_e32 v93, v128, v93
	v_mul_f32_e32 v90, v128, v90
	v_mul_f32_e32 v91, v128, v91
	v_mul_f32_e32 v88, v128, v88
	v_mul_f32_e32 v89, v128, v89
	v_mul_f32_e32 v86, v128, v86
	v_mul_f32_e32 v87, v128, v87
	v_mul_f32_e32 v84, v128, v84
	v_mul_f32_e32 v85, v128, v85
	v_mul_f32_e32 v82, v128, v82
	v_mul_f32_e32 v83, v128, v83
	v_mul_f32_e32 v80, v128, v80
	v_mul_f32_e32 v81, v128, v81
	v_mul_f32_e32 v62, v128, v62
	v_mul_f32_e32 v63, v128, v63
	v_mul_f32_e32 v60, v128, v60
	v_mul_f32_e32 v61, v128, v61
	v_mul_f32_e32 v58, v128, v58
	v_mul_f32_e32 v59, v128, v59
	v_mul_f32_e32 v56, v128, v56
	v_mul_f32_e32 v57, v128, v57
	v_mul_f32_e32 v54, v128, v54
	v_mul_f32_e32 v55, v128, v55
	v_mul_f32_e32 v52, v128, v52
	v_mul_f32_e32 v53, v128, v53
	v_mul_f32_e32 v50, v128, v50
	v_mul_f32_e32 v51, v128, v51
	v_mul_f32_e32 v48, v128, v48
	v_mul_f32_e32 v49, v128, v49
	v_mul_f32_e32 v30, v128, v30
	v_mul_f32_e32 v31, v128, v31
	v_mul_f32_e32 v28, v128, v28
	v_mul_f32_e32 v29, v128, v29
	v_mul_f32_e32 v26, v128, v26
	v_mul_f32_e32 v27, v128, v27
	v_mul_f32_e32 v24, v128, v24
	v_mul_f32_e32 v25, v128, v25
	v_mul_f32_e32 v22, v128, v22
	v_mul_f32_e32 v23, v128, v23
	v_mul_f32_e32 v20, v128, v20
	v_mul_f32_e32 v21, v128, v21
	v_mul_f32_e32 v18, v128, v18
	v_mul_f32_e32 v19, v128, v19
	v_mul_f32_e32 v16, v128, v16
	v_mul_f32_e32 v17, v128, v17

.LBB0_1081:
	s_bitcmp1_b32 s52, 0
	s_cselect_b32 s4, 0x9400, 0
	s_add_i32 s6, s4, 0
	s_add_i32 s4, s6, s37
	v_add3_u32 v190, s4, v180, v233
	ds_read_b128 v[144:147], v195 offset:4608
	ds_read_b128 v[148:151], v190
	ds_read_b128 v[196:199], v195 offset:4640
	ds_read_b128 v[152:155], v190 offset:32
	ds_read_b128 v[200:203], v195 offset:4672
	ds_read_b128 v[156:159], v190 offset:64
	ds_read_b128 v[204:207], v195 offset:4704
	ds_read_b128 v[208:211], v190 offset:96
	ds_read_b128 v[212:215], v190 offset:8704
	ds_read_b128 v[216:219], v190 offset:8736
	ds_read_b128 v[220:223], v190 offset:8768
	ds_read_b128 v[224:227], v190 offset:8800
	s_add_i32 s7, s53, 0xffffffbf
	s_mov_b64 s[4:5], -1
	s_cmp_le_u32 s7, s41
	s_waitcnt lgkmcnt(10)
	v_mfma_f32_32x32x16_bf16 v[128:143], v[148:151], v[144:147], 0
	s_waitcnt lgkmcnt(8)
	v_mfma_f32_32x32x16_bf16 v[128:143], v[152:155], v[196:199], v[128:143]
	s_waitcnt lgkmcnt(6)
	v_mfma_f32_32x32x16_bf16 v[128:143], v[156:159], v[200:203], v[128:143]
	s_waitcnt lgkmcnt(4)
	v_mfma_f32_32x32x16_bf16 v[128:143], v[208:211], v[204:207], v[128:143]
	s_waitcnt lgkmcnt(3)
	v_mfma_f32_32x32x16_bf16 v[144:159], v[212:215], v[144:147], 0
	s_waitcnt lgkmcnt(2)
	v_mfma_f32_32x32x16_bf16 v[144:159], v[216:219], v[196:199], v[144:159]
	s_waitcnt lgkmcnt(1)
	v_mfma_f32_32x32x16_bf16 v[144:159], v[220:223], v[200:203], v[144:159]
	s_waitcnt lgkmcnt(0)
	v_mfma_f32_32x32x16_bf16 v[144:159], v[224:227], v[204:207], v[144:159]
	s_cbranch_scc0 .LBB0_1083
	s_add_i32 s4, 0, 0x27a00
	v_mov_b32_e32 v190, s4
	ds_read_b32 v190, v190
	s_mov_b64 s[4:5], 0
	v_mbcnt_lo_u32_b32 v191, -1, 0
	v_mbcnt_hi_u32_b32 v191, -1, v191
	v_lshlrev_b32_e32 v191, 2, v191
	v_xor_b32_e32 v191, 0x80, v191
	v_max3_f32 v196, v128, v129, v130
	v_max3_f32 v196, v196, v131, v132
	v_max3_f32 v196, v196, v133, v134
	v_max3_f32 v196, v196, v135, v136
	v_max3_f32 v196, v196, v137, v138
	v_max3_f32 v196, v196, v139, v140
	v_max3_f32 v196, v196, v141, v142
	v_max3_f32 v196, v196, v143, v144
	v_max3_f32 v196, v196, v145, v146
	v_max3_f32 v196, v196, v147, v148
	v_max3_f32 v196, v196, v149, v150
	v_max3_f32 v196, v196, v151, v152
	v_max3_f32 v196, v196, v153, v154
	v_max3_f32 v196, v196, v155, v156
	v_max3_f32 v196, v196, v157, v158
	v_max_f32_e32 v196, v196, v159
	ds_bpermute_b32 v191, v191, v196
	s_waitcnt lgkmcnt(0)
	v_max_f32_e32 v196, v196, v191
	v_fma_f32 v196, v196, s28, v190
	v_add_f32_e32 v197, 0x41000000, v188
	v_cmp_gt_f32_e32 vcc, v196, v197
	s_cbranch_vccz .Lat_far_nors_2
	v_max_f32_e32 v197, v188, v196
	v_sub_f32_e32 v198, v188, v197
	v_exp_f32_e32 v198, v198
	v_mov_b32_e32 v188, v197
	v_mul_f32_e32 v237, v237, v198
	v_mul_f32_e32 v110, v198, v110
	v_mul_f32_e32 v111, v198, v111
	v_mul_f32_e32 v108, v198, v108
	v_mul_f32_e32 v109, v198, v109
	v_mul_f32_e32 v106, v198, v106
	v_mul_f32_e32 v107, v198, v107
	v_mul_f32_e32 v104, v198, v104
	v_mul_f32_e32 v105, v198, v105
	v_mul_f32_e32 v102, v198, v102
	v_mul_f32_e32 v103, v198, v103
	v_mul_f32_e32 v100, v198, v100
	v_mul_f32_e32 v101, v198, v101
	v_mul_f32_e32 v98, v198, v98
	v_mul_f32_e32 v99, v198, v99
	v_mul_f32_e32 v96, v198, v96
	v_mul_f32_e32 v97, v198, v97
	v_mul_f32_e32 v78, v198, v78
	v_mul_f32_e32 v79, v198, v79
	v_mul_f32_e32 v76, v198, v76
	v_mul_f32_e32 v77, v198, v77
	v_mul_f32_e32 v74, v198, v74
	v_mul_f32_e32 v75, v198, v75
	v_mul_f32_e32 v72, v198, v72
	v_mul_f32_e32 v73, v198, v73
	v_mul_f32_e32 v70, v198, v70
	v_mul_f32_e32 v71, v198, v71
	v_mul_f32_e32 v68, v198, v68
	v_mul_f32_e32 v69, v198, v69
	v_mul_f32_e32 v66, v198, v66
	v_mul_f32_e32 v67, v198, v67
	v_mul_f32_e32 v64, v198, v64
	v_mul_f32_e32 v65, v198, v65
	v_mul_f32_e32 v46, v198, v46
	v_mul_f32_e32 v47, v198, v47
	v_mul_f32_e32 v44, v198, v44
	v_mul_f32_e32 v45, v198, v45
	v_mul_f32_e32 v42, v198, v42
	v_mul_f32_e32 v43, v198, v43
	v_mul_f32_e32 v40, v198, v40
	v_mul_f32_e32 v41, v198, v41
	v_mul_f32_e32 v38, v198, v38
	v_mul_f32_e32 v39, v198, v39
	v_mul_f32_e32 v36, v198, v36
	v_mul_f32_e32 v37, v198, v37
	v_mul_f32_e32 v34, v198, v34
	v_mul_f32_e32 v35, v198, v35
	v_mul_f32_e32 v32, v198, v32
	v_mul_f32_e32 v33, v198, v33
	v_mul_f32_e32 v14, v198, v14
	v_mul_f32_e32 v15, v198, v15
	v_mul_f32_e32 v12, v198, v12
	v_mul_f32_e32 v13, v198, v13
	v_mul_f32_e32 v10, v198, v10
	v_mul_f32_e32 v11, v198, v11
	v_mul_f32_e32 v8, v198, v8
	v_mul_f32_e32 v9, v198, v9
	v_mul_f32_e32 v6, v198, v6
	v_mul_f32_e32 v7, v198, v7
	v_mul_f32_e32 v4, v198, v4
	v_mul_f32_e32 v5, v198, v5
	v_mul_f32_e32 v2, v198, v2
	v_mul_f32_e32 v3, v198, v3
	v_mul_f32_e32 v0, v198, v0
	v_mul_f32_e32 v1, v198, v1

.LBB0_1085:
	s_nop 0
	v_max_f32_e32 v128, v227, v227
	v_max_f32_e32 v129, v226, v226
	v_max_f32_e32 v128, v129, v128
	v_max3_f32 v128, v128, v224, v225
	v_max3_f32 v128, v128, v222, v223
	v_max3_f32 v128, v128, v220, v221
	v_max3_f32 v128, v128, v218, v219
	v_max3_f32 v128, v128, v216, v217
	v_max3_f32 v128, v128, v214, v215
	v_max3_f32 v128, v128, v212, v213
	v_max3_f32 v128, v128, v210, v211
	v_max3_f32 v128, v128, v208, v209
	v_max3_f32 v128, v128, v206, v207
	v_max3_f32 v128, v128, v204, v205
	v_max3_f32 v128, v128, v202, v203
	v_max3_f32 v128, v128, v200, v201
	v_mbcnt_lo_u32_b32 v129, -1, 0
	v_mbcnt_hi_u32_b32 v129, -1, v129
	v_max3_f32 v128, v128, v198, v199
	v_lshlrev_b32_e32 v129, 2, v129
	v_max3_f32 v128, v128, v196, v197
	v_xor_b32_e32 v129, 0x80, v129
	ds_bpermute_b32 v129, v129, v128
	s_waitcnt lgkmcnt(0)
	v_max_f32_e32 v129, v129, v129
	v_max_f32_e32 v128, v128, v129
	v_add_f32_e32 v129, 0x41000000, v188
	v_cmp_gt_f32_e32 vcc, v128, v129
	s_cbranch_vccz .LBB0_1087
	v_max_f32_e32 v128, v128, v128
	v_max_f32_e32 v129, v188, v188
	v_max_f32_e32 v129, v129, v128
	v_sub_f32_e32 v128, v188, v129
	v_exp_f32_e32 v128, v128
	v_mov_b32_e32 v188, v129
	v_mul_f32_e32 v237, v237, v128
	v_mul_f32_e32 v110, v128, v110
	v_mul_f32_e32 v111, v128, v111
	v_mul_f32_e32 v108, v128, v108
	v_mul_f32_e32 v109, v128, v109
	v_mul_f32_e32 v106, v128, v106
	v_mul_f32_e32 v107, v128, v107
	v_mul_f32_e32 v104, v128, v104
	v_mul_f32_e32 v105, v128, v105
	v_mul_f32_e32 v102, v128, v102
	v_mul_f32_e32 v103, v128, v103
	v_mul_f32_e32 v100, v128, v100
	v_mul_f32_e32 v101, v128, v101
	v_mul_f32_e32 v98, v128, v98
	v_mul_f32_e32 v99, v128, v99
	v_mul_f32_e32 v96, v128, v96
	v_mul_f32_e32 v97, v128, v97
	v_mul_f32_e32 v78, v128, v78
	v_mul_f32_e32 v79, v128, v79
	v_mul_f32_e32 v76, v128, v76
	v_mul_f32_e32 v77, v128, v77
	v_mul_f32_e32 v74, v128, v74
	v_mul_f32_e32 v75, v128, v75
	v_mul_f32_e32 v72, v128, v72
	v_mul_f32_e32 v73, v128, v73
	v_mul_f32_e32 v70, v128, v70
	v_mul_f32_e32 v71, v128, v71
	v_mul_f32_e32 v68, v128, v68
	v_mul_f32_e32 v69, v128, v69
	v_mul_f32_e32 v66, v128, v66
	v_mul_f32_e32 v67, v128, v67
	v_mul_f32_e32 v64, v128, v64
	v_mul_f32_e32 v65, v128, v65
	v_mul_f32_e32 v46, v128, v46
	v_mul_f32_e32 v47, v128, v47
	v_mul_f32_e32 v44, v128, v44
	v_mul_f32_e32 v45, v128, v45
	v_mul_f32_e32 v42, v128, v42
	v_mul_f32_e32 v43, v128, v43
	v_mul_f32_e32 v40, v128, v40
	v_mul_f32_e32 v41, v128, v41
	v_mul_f32_e32 v38, v128, v38
	v_mul_f32_e32 v39, v128, v39
	v_mul_f32_e32 v36, v128, v36
	v_mul_f32_e32 v37, v128, v37
	v_mul_f32_e32 v34, v128, v34
	v_mul_f32_e32 v35, v128, v35
	v_mul_f32_e32 v32, v128, v32
	v_mul_f32_e32 v33, v128, v33
	v_mul_f32_e32 v14, v128, v14
	v_mul_f32_e32 v15, v128, v15
	v_mul_f32_e32 v12, v128, v12
	v_mul_f32_e32 v13, v128, v13
	v_mul_f32_e32 v10, v128, v10
	v_mul_f32_e32 v11, v128, v11
	v_mul_f32_e32 v8, v128, v8
	v_mul_f32_e32 v9, v128, v9
	v_mul_f32_e32 v6, v128, v6
	v_mul_f32_e32 v7, v128, v7
	v_mul_f32_e32 v4, v128, v4
	v_mul_f32_e32 v5, v128, v5
	v_mul_f32_e32 v2, v128, v2
	v_mul_f32_e32 v3, v128, v3
	v_mul_f32_e32 v0, v128, v0
	v_mul_f32_e32 v1, v128, v1
